# k7 merge epilogue loads batched + LayerNorm wave sums via DPP instead of ds_bpermute chains
# baseline (speedup 1.0000x reference)
.LBB0_88:
	s_waitcnt vmcnt(3)
	v_lshlrev_b32_e32 v32, 16, v56
	v_and_b32_e32 v33, 0xffff0000, v56
	v_add_f32_e32 v34, 0, v32
	v_add_f32_e32 v36, v34, v33
	v_lshlrev_b32_e32 v34, 16, v57
	v_and_b32_e32 v35, 0xffff0000, v57
	v_add_f32_e32 v36, v36, v34
	v_add_f32_e32 v38, v36, v35
	s_waitcnt vmcnt(2)
	v_lshlrev_b32_e32 v36, 16, v58
	v_and_b32_e32 v37, 0xffff0000, v58
	v_add_f32_e32 v38, v38, v36
	v_add_f32_e32 v40, v38, v37
	v_lshlrev_b32_e32 v38, 16, v59
	v_and_b32_e32 v39, 0xffff0000, v59
	v_add_f32_e32 v40, v40, v38
	v_add_f32_e32 v42, v40, v39
	s_waitcnt vmcnt(1)
	v_lshlrev_b32_e32 v40, 16, v60
	v_and_b32_e32 v41, 0xffff0000, v60
	v_add_f32_e32 v42, v42, v40
	v_add_f32_e32 v44, v42, v41
	v_lshlrev_b32_e32 v42, 16, v61
	v_and_b32_e32 v43, 0xffff0000, v61
	v_add_f32_e32 v44, v44, v42
	v_add_f32_e32 v46, v44, v43
	s_waitcnt vmcnt(0)
	v_lshlrev_b32_e32 v44, 16, v62
	v_and_b32_e32 v45, 0xffff0000, v62
	v_add_f32_e32 v46, v46, v44
	v_add_f32_e32 v56, v46, v45
	v_lshlrev_b32_e32 v46, 16, v63
	v_and_b32_e32 v47, 0xffff0000, v63
	v_add_f32_e32 v56, v56, v46
	v_add_f32_e32 v56, v56, v47
	v_add_u32_e32 v69, s6, v54
	s_mov_b32 s0, 0x800000
	s_nop 1
	v_add_f32_dpp v56, v56, v56 quad_perm:[1,0,3,2] row_mask:0xf bank_mask:0xf
	s_nop 1
	v_add_f32_dpp v56, v56, v56 quad_perm:[2,3,0,1] row_mask:0xf bank_mask:0xf
	s_nop 1
	v_add_f32_dpp v56, v56, v56 row_half_mirror row_mask:0xf bank_mask:0xf
	s_nop 1
	v_add_f32_dpp v58, v56, v56 row_mirror row_mask:0xf bank_mask:0xf
	v_min_i32_e32 v56, 0x401f, v69
	v_ashrrev_i32_e32 v57, 31, v56
	v_lshlrev_b64 v[56:57], 11, v[56:57]
	v_lshl_add_u64 v[62:63], v[48:49], 0, v[56:57]
	s_nop 1
	v_add_f32_dpp v70, v58, v58 row_bcast:15 row_mask:0xa bank_mask:0xf
	global_load_dwordx2 v[56:57], v[62:63], off
	global_load_dwordx2 v[58:59], v[62:63], off offset:512
	global_load_dwordx2 v[60:61], v[62:63], off offset:1024
	s_nop 0
	global_load_dwordx2 v[62:63], v[62:63], off offset:1536
	s_nop 1
	v_add_f32_dpp v70, v70, v70 row_bcast:31 row_mask:0xc bank_mask:0xf
	s_nop 0
	v_readlane_b32 s100, v70, 63
	s_nop 1
	v_mov_b32_e32 v70, s100
	v_mul_f32_e32 v70, 0x3a800000, v70
	v_pk_add_f32 v[32:33], v[32:33], v[70:71] op_sel_hi:[1,0] neg_lo:[0,1] neg_hi:[0,1]
	v_pk_add_f32 v[34:35], v[34:35], v[70:71] op_sel_hi:[1,0] neg_lo:[0,1] neg_hi:[0,1]
	v_pk_mul_f32 v[72:73], v[32:33], v[32:33]
	v_pk_mul_f32 v[74:75], v[34:35], v[34:35]
	v_add_f32_e32 v72, v72, v73
	v_pk_add_f32 v[36:37], v[36:37], v[70:71] op_sel_hi:[1,0] neg_lo:[0,1] neg_hi:[0,1]
	v_add_f32_e32 v72, v74, v72
	v_pk_mul_f32 v[76:77], v[36:37], v[36:37]
	v_add_f32_e32 v72, v75, v72
	v_pk_add_f32 v[38:39], v[38:39], v[70:71] op_sel_hi:[1,0] neg_lo:[0,1] neg_hi:[0,1]
	v_add_f32_e32 v72, v76, v72
	v_pk_mul_f32 v[78:79], v[38:39], v[38:39]
	v_add_f32_e32 v72, v77, v72
	v_pk_add_f32 v[40:41], v[40:41], v[70:71] op_sel_hi:[1,0] neg_lo:[0,1] neg_hi:[0,1]
	v_add_f32_e32 v72, v78, v72
	v_pk_mul_f32 v[80:81], v[40:41], v[40:41]
	v_add_f32_e32 v72, v79, v72
	v_pk_add_f32 v[42:43], v[42:43], v[70:71] op_sel_hi:[1,0] neg_lo:[0,1] neg_hi:[0,1]
	v_add_f32_e32 v72, v80, v72
	v_pk_mul_f32 v[82:83], v[42:43], v[42:43]
	v_add_f32_e32 v72, v81, v72
	v_pk_add_f32 v[84:85], v[44:45], v[70:71] op_sel_hi:[1,0] neg_lo:[0,1] neg_hi:[0,1]
	v_add_f32_e32 v72, v82, v72
	v_pk_mul_f32 v[44:45], v[84:85], v[84:85]
	v_add_f32_e32 v72, v83, v72
	v_pk_add_f32 v[70:71], v[46:47], v[70:71] op_sel_hi:[1,0] neg_lo:[0,1] neg_hi:[0,1]
	v_add_f32_e32 v44, v44, v72
	v_pk_mul_f32 v[46:47], v[70:71], v[70:71]
	v_add_f32_e32 v44, v45, v44
	v_add_f32_e32 v44, v46, v44
	v_add_f32_e32 v44, v47, v44
	s_nop 1
	v_add_f32_dpp v44, v44, v44 quad_perm:[1,0,3,2] row_mask:0xf bank_mask:0xf
	s_nop 1
	v_add_f32_dpp v44, v44, v44 quad_perm:[2,3,0,1] row_mask:0xf bank_mask:0xf
	s_nop 1
	v_add_f32_dpp v44, v44, v44 row_half_mirror row_mask:0xf bank_mask:0xf
	s_nop 1
	v_add_f32_dpp v44, v44, v44 row_mirror row_mask:0xf bank_mask:0xf
	s_nop 1
	v_add_f32_dpp v44, v44, v44 row_bcast:15 row_mask:0xa bank_mask:0xf
	s_nop 1
	v_add_f32_dpp v44, v44, v44 row_bcast:31 row_mask:0xc bank_mask:0xf
	s_nop 0
	v_readlane_b32 s100, v44, 63
	s_nop 1
	v_mov_b32_e32 v44, s100
	v_fmamk_f32 v44, v44, 0x3a800000, v196
	v_mul_f32_e32 v45, 0x4b800000, v44
	v_cmp_gt_f32_e32 vcc, s0, v44
	s_nop 1
	v_cndmask_b32_e32 v44, v44, v45, vcc
	v_rsq_f32_e32 v44, v44
	s_nop 0
	v_mul_f32_e32 v45, 0x45800000, v44
	v_cndmask_b32_e32 v72, v44, v45, vcc
	v_pk_mul_f32 v[32:33], v[32:33], v[72:73] op_sel_hi:[1,0]
	v_pk_mul_f32 v[34:35], v[34:35], v[72:73] op_sel_hi:[1,0]
	v_pk_mul_f32 v[36:37], v[36:37], v[72:73] op_sel_hi:[1,0]
	v_pk_mul_f32 v[38:39], v[38:39], v[72:73] op_sel_hi:[1,0]
	v_pk_mul_f32 v[74:75], v[40:41], v[72:73] op_sel_hi:[1,0]
	v_pk_mul_f32 v[76:77], v[42:43], v[72:73] op_sel_hi:[1,0]
	v_pk_fma_f32 v[44:45], v[0:1], v[32:33], v[8:9]
	v_pk_fma_f32 v[46:47], v[2:3], v[34:35], v[10:11]
	v_pk_mul_f32 v[32:33], v[84:85], v[72:73] op_sel_hi:[1,0]
	v_pk_mul_f32 v[34:35], v[70:71], v[72:73] op_sel_hi:[1,0]
	v_pk_fma_f32 v[40:41], v[4:5], v[36:37], v[12:13]
	v_pk_fma_f32 v[42:43], v[6:7], v[38:39], v[14:15]
	v_pk_fma_f32 v[36:37], v[16:17], v[74:75], v[24:25]
	v_pk_fma_f32 v[38:39], v[18:19], v[76:77], v[26:27]
	v_pk_fma_f32 v[32:33], v[20:21], v[32:33], v[28:29]
	v_pk_fma_f32 v[34:35], v[22:23], v[34:35], v[30:31]
	s_and_b64 vcc, exec, s[10:11]
	s_cbranch_vccz .LBB0_92
	s_movk_i32 s0, 0x200f
	v_cmp_lt_i32_e32 vcc, s0, v54
	s_nop 1
	v_cndmask_b32_e32 v70, 0, v208, vcc
	v_add_u32_e32 v54, v70, v54
	v_cmp_lt_i32_e64 s[0:1], 15, v54
	s_and_saveexec_b64 s[14:15], s[0:1]
	s_cbranch_execz .LBB0_91
	v_cndmask_b32_e32 v70, 0, v209, vcc
	v_add3_u32 v176, v54, v70, -16
	v_lshlrev_b64 v[70:71], 12, v[176:177]
	v_lshl_add_u64 v[70:71], v[50:51], 0, v[70:71]
	global_store_dwordx4 v[70:71], v[44:47], off
	global_store_dwordx4 v[70:71], v[40:43], off offset:1024
	global_store_dwordx4 v[70:71], v[36:39], off offset:2048
	global_store_dwordx4 v[70:71], v[32:35], off offset:3072

.LBB0_190:
	s_waitcnt vmcnt(3)
	v_lshlrev_b32_e32 v51, 16, v44
	v_and_b32_e32 v60, 0xffff0000, v44
	v_add_f32_e32 v44, 0, v51
	v_lshlrev_b32_e32 v61, 16, v45
	v_add_f32_e32 v44, v44, v60
	v_and_b32_e32 v62, 0xffff0000, v45
	v_add_f32_e32 v44, v44, v61
	v_add_u32_e32 v32, s2, v32
	s_waitcnt vmcnt(2)
	v_lshlrev_b32_e32 v63, 16, v42
	v_add_f32_e32 v56, v44, v62
	v_and_b32_e32 v64, 0xffff0000, v42
	v_lshlrev_b32_e32 v65, 16, v43
	v_and_b32_e32 v66, 0xffff0000, v43
	s_waitcnt vmcnt(0)
	v_and_b32_e32 v42, 0xffff0000, v38
	v_lshlrev_b32_e32 v43, 16, v38
	v_min_i32_e32 v38, 0x401f, v32
	v_add_f32_e32 v56, v56, v63
	v_lshlrev_b32_e32 v67, 16, v40
	v_and_b32_e32 v68, 0xffff0000, v40
	v_lshlrev_b32_e32 v69, 16, v41
	v_and_b32_e32 v70, 0xffff0000, v41
	v_and_b32_e32 v40, 0xffff0000, v39
	v_lshlrev_b32_e32 v41, 16, v39
	v_ashrrev_i32_e32 v39, 31, v38
	v_add_f32_e32 v56, v56, v64
	v_lshlrev_b64 v[38:39], 11, v[38:39]
	v_add_f32_e32 v56, v56, v65
	v_lshl_add_u64 v[38:39], v[34:35], 0, v[38:39]
	v_add_f32_e32 v56, v56, v66
	global_load_dwordx2 v[44:45], v[38:39], off
	global_load_dwordx2 v[52:53], v[38:39], off offset:512
	global_load_dwordx2 v[54:55], v[38:39], off offset:1024
	s_nop 0
	global_load_dwordx2 v[38:39], v[38:39], off offset:1536
	v_add_f32_e32 v56, v56, v67
	v_add_f32_e32 v56, v56, v68
	v_add_f32_e32 v56, v56, v69
	v_add_f32_e32 v56, v56, v70
	v_add_f32_e32 v56, v56, v43
	v_add_f32_e32 v56, v56, v42
	v_add_f32_e32 v56, v56, v41
	v_add_f32_e32 v56, v56, v40
	v_cmp_lt_i32_e32 vcc, s10, v32
	s_or_b64 s[6:7], vcc, s[6:7]
	s_nop 1
	v_add_f32_dpp v56, v56, v56 quad_perm:[1,0,3,2] row_mask:0xf bank_mask:0xf
	s_nop 1
	v_add_f32_dpp v56, v56, v56 quad_perm:[2,3,0,1] row_mask:0xf bank_mask:0xf
	s_nop 1
	v_add_f32_dpp v56, v56, v56 row_half_mirror row_mask:0xf bank_mask:0xf
	s_nop 1
	v_add_f32_dpp v56, v56, v56 row_mirror row_mask:0xf bank_mask:0xf
	s_nop 1
	v_add_f32_dpp v56, v56, v56 row_bcast:15 row_mask:0xa bank_mask:0xf
	s_nop 1
	v_add_f32_dpp v57, v56, v56 row_bcast:31 row_mask:0xc bank_mask:0xf
	s_nop 0
	v_readlane_b32 s100, v57, 63
	s_nop 1
	v_mov_b32_e32 v57, s100
	v_fmac_f32_e32 v60, 0xba800000, v57
	v_fmac_f32_e32 v51, 0xba800000, v57
	v_mul_f32_e32 v71, v60, v60
	v_fmac_f32_e32 v61, 0xba800000, v57
	v_fmac_f32_e32 v71, v51, v51
	v_fmac_f32_e32 v62, 0xba800000, v57
	v_fmac_f32_e32 v71, v61, v61
	v_fmac_f32_e32 v63, 0xba800000, v57
	v_fmac_f32_e32 v71, v62, v62
	v_fmac_f32_e32 v64, 0xba800000, v57
	v_fmac_f32_e32 v71, v63, v63
	v_fmac_f32_e32 v65, 0xba800000, v57
	v_fmac_f32_e32 v71, v64, v64
	v_fmac_f32_e32 v66, 0xba800000, v57
	v_fmac_f32_e32 v71, v65, v65
	v_fmac_f32_e32 v67, 0xba800000, v57
	v_fmac_f32_e32 v71, v66, v66
	v_fmac_f32_e32 v68, 0xba800000, v57
	v_fmac_f32_e32 v71, v67, v67
	v_mul_f32_e32 v56, 0x3a800000, v57
	v_fmac_f32_e32 v69, 0xba800000, v57
	v_fmac_f32_e32 v71, v68, v68
	v_fmac_f32_e32 v70, 0xba800000, v57
	v_pk_add_f32 v[58:59], v[42:43], v[56:57] op_sel_hi:[1,0] neg_lo:[0,1] neg_hi:[0,1]
	v_fmac_f32_e32 v71, v69, v69
	v_pk_add_f32 v[56:57], v[40:41], v[56:57] op_sel_hi:[1,0] neg_lo:[0,1] neg_hi:[0,1]
	v_pk_mul_f32 v[40:41], v[58:59], v[58:59]
	v_fmac_f32_e32 v71, v70, v70
	v_add_f32_e32 v41, v41, v71
	v_pk_mul_f32 v[42:43], v[56:57], v[56:57]
	v_add_f32_e32 v40, v40, v41
	v_add_f32_e32 v40, v43, v40
	v_add_f32_e32 v40, v42, v40
	s_waitcnt vmcnt(2)
	v_mov_b64_e32 v[42:43], v[52:53]
	s_nop 1
	v_add_f32_dpp v40, v40, v40 quad_perm:[1,0,3,2] row_mask:0xf bank_mask:0xf
	s_nop 1
	v_add_f32_dpp v71, v40, v40 quad_perm:[2,3,0,1] row_mask:0xf bank_mask:0xf
	s_waitcnt vmcnt(1)
	v_mov_b64_e32 v[40:41], v[54:55]
	s_nop 1
	v_add_f32_dpp v52, v71, v71 row_half_mirror row_mask:0xf bank_mask:0xf
	s_nop 1
	v_add_f32_dpp v52, v52, v52 row_mirror row_mask:0xf bank_mask:0xf
	s_nop 1
	v_add_f32_dpp v52, v52, v52 row_bcast:15 row_mask:0xa bank_mask:0xf
	s_nop 1
	v_add_f32_dpp v52, v52, v52 row_bcast:31 row_mask:0xc bank_mask:0xf
	s_nop 0
	v_readlane_b32 s100, v52, 63
	s_nop 1
	v_mov_b32_e32 v52, s100
	v_fmamk_f32 v52, v52, 0x3a800000, v196
	v_mul_f32_e32 v53, 0x4b800000, v52
	v_cmp_gt_f32_e32 vcc, s8, v52
	s_nop 1
	v_cndmask_b32_e32 v52, v52, v53, vcc
	v_rsq_f32_e32 v52, v52
	s_nop 0
	v_mul_f32_e32 v53, 0x45800000, v52
	v_cndmask_b32_e32 v52, v52, v53, vcc
	v_mul_f32_e32 v53, v60, v52
	v_mul_f32_e32 v51, v51, v52
	v_mul_f32_e32 v54, v61, v52
	v_mul_f32_e32 v55, v62, v52
	v_mul_f32_e32 v60, v63, v52
	v_mul_f32_e32 v61, v64, v52
	v_mul_f32_e32 v62, v65, v52
	v_mul_f32_e32 v63, v66, v52
	v_mul_f32_e32 v64, v67, v52
	v_mul_f32_e32 v65, v68, v52
	v_mul_f32_e32 v66, v69, v52
	v_mul_f32_e32 v67, v70, v52
	v_mul_f32_e32 v59, v59, v52
	v_mul_f32_e32 v58, v58, v52
	v_mul_f32_e32 v57, v57, v52
	v_mul_f32_e32 v52, v56, v52
	v_fma_f32 v53, v1, v53, v9
	v_fma_f32 v51, v0, v51, v8
	v_fma_f32 v54, v2, v54, v10
	v_fma_f32 v55, v3, v55, v11
	v_fma_f32 v56, v4, v60, v12
	v_fma_f32 v59, v20, v59, v28
	v_fma_f32 v58, v21, v58, v29
	v_fma_f32 v68, v23, v52, v31
	s_nop 1
	v_cvt_pk_bf16_f32 v52, v51, v53
	s_nop 1
	v_cvt_pk_bf16_f32 v53, v54, v55
	v_fma_f32 v60, v5, v61, v13
	v_fma_f32 v61, v6, v62, v14
	v_fma_f32 v62, v7, v63, v15
	v_fma_f32 v63, v16, v64, v24
	v_fma_f32 v64, v17, v65, v25
	v_fma_f32 v65, v18, v66, v26
	v_fma_f32 v66, v19, v67, v27
	v_fma_f32 v67, v22, v57, v30
	s_nop 1
	v_cvt_pk_bf16_f32 v54, v56, v60
	s_nop 1
	v_cvt_pk_bf16_f32 v55, v61, v62
	s_nop 1
	v_cvt_pk_bf16_f32 v56, v63, v64
	s_nop 1
	v_cvt_pk_bf16_f32 v57, v65, v66
	s_nop 1
	v_cvt_pk_bf16_f32 v58, v59, v58
	s_nop 1
	v_cvt_pk_bf16_f32 v59, v67, v68
	global_store_dwordx2 v[36:37], v[52:53], off offset:-1536
	global_store_dwordx2 v[36:37], v[54:55], off offset:-1024
	global_store_dwordx2 v[36:37], v[56:57], off offset:-512
	global_store_dwordx2 v[36:37], v[58:59], off
	v_lshl_add_u64 v[36:37], v[36:37], 0, s[4:5]
	s_andn2_b64 exec, exec, s[6:7]
	s_cbranch_execnz .LBB0_190

.LBB0_230:
	s_waitcnt vmcnt(15)
	v_lshlrev_b32_e32 v66, 16, v174
	v_and_b32_e32 v67, 0xffff0000, v174
	v_lshlrev_b32_e32 v64, 16, v173
	v_and_b32_e32 v65, 0xffff0000, v173
	s_waitcnt vmcnt(4)
	v_pk_mul_f32 v[62:63], v[62:63], v[66:67]
	v_cndmask_b32_e64 v66, 0, 1, s[2:3]
	v_cmp_ne_u32_e64 s[38:39], 1, v66
	s_andn2_b64 vcc, exec, s[2:3]
	v_pk_mul_f32 v[60:61], v[60:61], v[64:65]
	s_cbranch_vccnz .LBB0_232
	global_load_dwordx2 v[96:97], v[130:131], off
	global_load_dwordx2 v[98:99], v[130:131], off offset:32
	global_load_dwordx2 v[100:101], v[130:131], off offset:64
	global_load_dwordx2 v[102:103], v[130:131], off offset:96
	global_load_dwordx2 v[104:105], v[132:133], off
	global_load_dwordx2 v[106:107], v[132:133], off offset:32
	global_load_dwordx2 v[108:109], v[132:133], off offset:64
	global_load_dwordx2 v[110:111], v[132:133], off offset:96
	global_load_dwordx2 v[112:113], v[134:135], off
	global_load_dwordx2 v[114:115], v[134:135], off offset:32
	global_load_dwordx2 v[116:117], v[134:135], off offset:64
	global_load_dwordx2 v[118:119], v[134:135], off offset:96
	global_load_dwordx2 v[120:121], v[136:137], off
	global_load_dwordx2 v[122:123], v[136:137], off offset:32
	global_load_dwordx2 v[124:125], v[136:137], off offset:64
	global_load_dwordx2 v[126:127], v[136:137], off offset:96
	s_waitcnt vmcnt(15)
	v_lshlrev_b32_e32 v66, 16, v96
	v_and_b32_e32 v67, 0xffff0000, v96
	v_lshlrev_b32_e32 v64, 16, v97
	v_and_b32_e32 v65, 0xffff0000, v97
	v_pk_add_f32 v[62:63], v[62:63], v[64:65]
	v_pk_add_f32 v[60:61], v[60:61], v[66:67]
.LBB0_232:
	s_nop 0
	s_nop 1
	v_cvt_pk_bf16_f32 v60, v60, v61
	s_nop 1
	v_cvt_pk_bf16_f32 v61, v62, v63
	global_store_dwordx2 v[130:131], v[60:61], off
	v_lshlrev_b32_e32 v60, 16, v171
	v_and_b32_e32 v61, 0xffff0000, v171
	v_lshlrev_b32_e32 v62, 16, v172
	v_and_b32_e32 v63, 0xffff0000, v172
	v_pk_mul_f32 v[58:59], v[58:59], v[62:63]
	s_and_b64 vcc, exec, s[38:39]
	v_pk_mul_f32 v[56:57], v[56:57], v[60:61]
	s_cbranch_vccnz .LBB0_234
	s_waitcnt vmcnt(15)
	v_lshlrev_b32_e32 v62, 16, v98
	v_and_b32_e32 v63, 0xffff0000, v98
	v_lshlrev_b32_e32 v60, 16, v99
	v_and_b32_e32 v61, 0xffff0000, v99
	v_pk_add_f32 v[58:59], v[58:59], v[60:61]
	v_pk_add_f32 v[56:57], v[56:57], v[62:63]
.LBB0_234:
	s_nop 0
	s_nop 1
	v_cvt_pk_bf16_f32 v56, v56, v57
	s_nop 1
	v_cvt_pk_bf16_f32 v57, v58, v59
	global_store_dwordx2 v[130:131], v[56:57], off offset:32
	v_lshlrev_b32_e32 v56, 16, v169
	v_and_b32_e32 v57, 0xffff0000, v169
	v_lshlrev_b32_e32 v58, 16, v170
	v_and_b32_e32 v59, 0xffff0000, v170
	v_pk_mul_f32 v[54:55], v[54:55], v[58:59]
	s_and_b64 vcc, exec, s[38:39]
	v_pk_mul_f32 v[52:53], v[52:53], v[56:57]
	s_cbranch_vccnz .LBB0_236
	s_waitcnt vmcnt(15)
	v_lshlrev_b32_e32 v58, 16, v100
	v_and_b32_e32 v59, 0xffff0000, v100
	v_lshlrev_b32_e32 v56, 16, v101
	v_and_b32_e32 v57, 0xffff0000, v101
	v_pk_add_f32 v[54:55], v[54:55], v[56:57]
	v_pk_add_f32 v[52:53], v[52:53], v[58:59]
.LBB0_236:
	s_nop 0
	s_nop 1
	v_cvt_pk_bf16_f32 v52, v52, v53
	s_nop 1
	v_cvt_pk_bf16_f32 v53, v54, v55
	global_store_dwordx2 v[130:131], v[52:53], off offset:64
	v_lshlrev_b32_e32 v52, 16, v167
	v_and_b32_e32 v53, 0xffff0000, v167
	v_lshlrev_b32_e32 v54, 16, v168
	v_and_b32_e32 v55, 0xffff0000, v168
	v_pk_mul_f32 v[50:51], v[50:51], v[54:55]
	s_and_b64 vcc, exec, s[38:39]
	v_pk_mul_f32 v[48:49], v[48:49], v[52:53]
	s_cbranch_vccnz .LBB0_238
	s_waitcnt vmcnt(15)
	v_lshlrev_b32_e32 v54, 16, v102
	v_and_b32_e32 v55, 0xffff0000, v102
	v_lshlrev_b32_e32 v52, 16, v103
	v_and_b32_e32 v53, 0xffff0000, v103
	v_pk_add_f32 v[50:51], v[50:51], v[52:53]
	v_pk_add_f32 v[48:49], v[48:49], v[54:55]
.LBB0_238:
	s_nop 0
	s_nop 1
	v_cvt_pk_bf16_f32 v48, v48, v49
	s_nop 1
	v_cvt_pk_bf16_f32 v49, v50, v51
	global_store_dwordx2 v[130:131], v[48:49], off offset:96
	v_lshlrev_b32_e32 v48, 16, v165
	v_and_b32_e32 v49, 0xffff0000, v165
	v_lshlrev_b32_e32 v50, 16, v166
	v_and_b32_e32 v51, 0xffff0000, v166
	v_pk_mul_f32 v[46:47], v[46:47], v[50:51]
	s_and_b64 vcc, exec, s[38:39]
	v_pk_mul_f32 v[44:45], v[44:45], v[48:49]
	s_cbranch_vccnz .LBB0_240
	s_waitcnt vmcnt(15)
	v_lshlrev_b32_e32 v50, 16, v104
	v_and_b32_e32 v51, 0xffff0000, v104
	v_lshlrev_b32_e32 v48, 16, v105
	v_and_b32_e32 v49, 0xffff0000, v105
	v_pk_add_f32 v[46:47], v[46:47], v[48:49]
	v_pk_add_f32 v[44:45], v[44:45], v[50:51]
.LBB0_240:
	s_nop 0
	s_nop 1
	v_cvt_pk_bf16_f32 v44, v44, v45
	s_nop 1
	v_cvt_pk_bf16_f32 v45, v46, v47
	global_store_dwordx2 v[132:133], v[44:45], off
	v_lshlrev_b32_e32 v44, 16, v163
	v_and_b32_e32 v45, 0xffff0000, v163
	v_lshlrev_b32_e32 v46, 16, v164
	v_and_b32_e32 v47, 0xffff0000, v164
	v_pk_mul_f32 v[42:43], v[42:43], v[46:47]
	s_and_b64 vcc, exec, s[38:39]
	v_pk_mul_f32 v[40:41], v[40:41], v[44:45]
	s_cbranch_vccnz .LBB0_242
	s_waitcnt vmcnt(15)
	v_lshlrev_b32_e32 v46, 16, v106
	v_and_b32_e32 v47, 0xffff0000, v106
	v_lshlrev_b32_e32 v44, 16, v107
	v_and_b32_e32 v45, 0xffff0000, v107
	v_pk_add_f32 v[42:43], v[42:43], v[44:45]
	v_pk_add_f32 v[40:41], v[40:41], v[46:47]
.LBB0_242:
	s_nop 0
	s_nop 1
	v_cvt_pk_bf16_f32 v40, v40, v41
	s_nop 1
	v_cvt_pk_bf16_f32 v41, v42, v43
	global_store_dwordx2 v[132:133], v[40:41], off offset:32
	v_lshlrev_b32_e32 v40, 16, v161
	v_and_b32_e32 v41, 0xffff0000, v161
	v_lshlrev_b32_e32 v42, 16, v162
	v_and_b32_e32 v43, 0xffff0000, v162
	v_pk_mul_f32 v[38:39], v[38:39], v[42:43]
	s_and_b64 vcc, exec, s[38:39]
	v_pk_mul_f32 v[36:37], v[36:37], v[40:41]
	s_cbranch_vccnz .LBB0_244
	s_waitcnt vmcnt(15)
	v_lshlrev_b32_e32 v42, 16, v108
	v_and_b32_e32 v43, 0xffff0000, v108
	v_lshlrev_b32_e32 v40, 16, v109
	v_and_b32_e32 v41, 0xffff0000, v109
	v_pk_add_f32 v[38:39], v[38:39], v[40:41]
	v_pk_add_f32 v[36:37], v[36:37], v[42:43]
.LBB0_244:
	s_nop 0
	s_nop 1
	v_cvt_pk_bf16_f32 v36, v36, v37
	s_nop 1
	v_cvt_pk_bf16_f32 v37, v38, v39
	global_store_dwordx2 v[132:133], v[36:37], off offset:64
	v_lshlrev_b32_e32 v36, 16, v159
	v_and_b32_e32 v37, 0xffff0000, v159
	v_lshlrev_b32_e32 v38, 16, v160
	v_and_b32_e32 v39, 0xffff0000, v160
	v_pk_mul_f32 v[34:35], v[34:35], v[38:39]
	s_and_b64 vcc, exec, s[38:39]
	v_pk_mul_f32 v[32:33], v[32:33], v[36:37]
	s_cbranch_vccnz .LBB0_246
	s_waitcnt vmcnt(15)
	v_lshlrev_b32_e32 v38, 16, v110
	v_and_b32_e32 v39, 0xffff0000, v110
	v_lshlrev_b32_e32 v36, 16, v111
	v_and_b32_e32 v37, 0xffff0000, v111
	v_pk_add_f32 v[34:35], v[34:35], v[36:37]
	v_pk_add_f32 v[32:33], v[32:33], v[38:39]
.LBB0_246:
	s_nop 0
	s_nop 1
	v_cvt_pk_bf16_f32 v32, v32, v33
	s_nop 1
	v_cvt_pk_bf16_f32 v33, v34, v35
	global_store_dwordx2 v[132:133], v[32:33], off offset:96
	v_lshlrev_b32_e32 v32, 16, v157
	v_and_b32_e32 v33, 0xffff0000, v157
	v_lshlrev_b32_e32 v34, 16, v158
	v_and_b32_e32 v35, 0xffff0000, v158
	v_pk_mul_f32 v[30:31], v[30:31], v[34:35]
	s_and_b64 vcc, exec, s[38:39]
	v_pk_mul_f32 v[28:29], v[28:29], v[32:33]
	s_cbranch_vccnz .LBB0_248
	s_waitcnt vmcnt(15)
	v_lshlrev_b32_e32 v34, 16, v112
	v_and_b32_e32 v35, 0xffff0000, v112
	v_lshlrev_b32_e32 v32, 16, v113
	v_and_b32_e32 v33, 0xffff0000, v113
	v_pk_add_f32 v[30:31], v[30:31], v[32:33]
	v_pk_add_f32 v[28:29], v[28:29], v[34:35]
.LBB0_248:
	s_nop 0
	s_nop 1
	v_cvt_pk_bf16_f32 v28, v28, v29
	s_nop 1
	v_cvt_pk_bf16_f32 v29, v30, v31
	global_store_dwordx2 v[134:135], v[28:29], off
	v_lshlrev_b32_e32 v28, 16, v155
	v_and_b32_e32 v29, 0xffff0000, v155
	v_lshlrev_b32_e32 v30, 16, v156
	v_and_b32_e32 v31, 0xffff0000, v156
	v_pk_mul_f32 v[26:27], v[26:27], v[30:31]
	s_and_b64 vcc, exec, s[38:39]
	v_pk_mul_f32 v[24:25], v[24:25], v[28:29]
	s_cbranch_vccnz .LBB0_250
	s_waitcnt vmcnt(15)
	v_lshlrev_b32_e32 v30, 16, v114
	v_and_b32_e32 v31, 0xffff0000, v114
	v_lshlrev_b32_e32 v28, 16, v115
	v_and_b32_e32 v29, 0xffff0000, v115
	v_pk_add_f32 v[26:27], v[26:27], v[28:29]
	v_pk_add_f32 v[24:25], v[24:25], v[30:31]
.LBB0_250:
	s_nop 0
	s_nop 1
	v_cvt_pk_bf16_f32 v24, v24, v25
	s_nop 1
	v_cvt_pk_bf16_f32 v25, v26, v27
	global_store_dwordx2 v[134:135], v[24:25], off offset:32
	v_lshlrev_b32_e32 v24, 16, v153
	v_and_b32_e32 v25, 0xffff0000, v153
	v_lshlrev_b32_e32 v26, 16, v154
	v_and_b32_e32 v27, 0xffff0000, v154
	v_pk_mul_f32 v[22:23], v[22:23], v[26:27]
	s_and_b64 vcc, exec, s[38:39]
	v_pk_mul_f32 v[20:21], v[20:21], v[24:25]
	s_cbranch_vccnz .LBB0_252
	s_waitcnt vmcnt(15)
	v_lshlrev_b32_e32 v26, 16, v116
	v_and_b32_e32 v27, 0xffff0000, v116
	v_lshlrev_b32_e32 v24, 16, v117
	v_and_b32_e32 v25, 0xffff0000, v117
	v_pk_add_f32 v[22:23], v[22:23], v[24:25]
	v_pk_add_f32 v[20:21], v[20:21], v[26:27]
.LBB0_252:
	s_nop 0
	s_nop 1
	v_cvt_pk_bf16_f32 v20, v20, v21
	s_nop 1
	v_cvt_pk_bf16_f32 v21, v22, v23
	global_store_dwordx2 v[134:135], v[20:21], off offset:64
	v_lshlrev_b32_e32 v20, 16, v151
	v_and_b32_e32 v21, 0xffff0000, v151
	v_lshlrev_b32_e32 v22, 16, v152
	v_and_b32_e32 v23, 0xffff0000, v152
	v_pk_mul_f32 v[18:19], v[18:19], v[22:23]
	s_and_b64 vcc, exec, s[38:39]
	v_pk_mul_f32 v[16:17], v[16:17], v[20:21]
	s_cbranch_vccnz .LBB0_254
	s_waitcnt vmcnt(15)
	v_lshlrev_b32_e32 v22, 16, v118
	v_and_b32_e32 v23, 0xffff0000, v118
	v_lshlrev_b32_e32 v20, 16, v119
	v_and_b32_e32 v21, 0xffff0000, v119
	v_pk_add_f32 v[18:19], v[18:19], v[20:21]
	v_pk_add_f32 v[16:17], v[16:17], v[22:23]
.LBB0_254:
	s_nop 0
	s_nop 1
	v_cvt_pk_bf16_f32 v16, v16, v17
	s_nop 1
	v_cvt_pk_bf16_f32 v17, v18, v19
	global_store_dwordx2 v[134:135], v[16:17], off offset:96
	v_lshlrev_b32_e32 v16, 16, v149
	v_and_b32_e32 v17, 0xffff0000, v149
	v_lshlrev_b32_e32 v18, 16, v150
	v_and_b32_e32 v19, 0xffff0000, v150
	v_pk_mul_f32 v[14:15], v[14:15], v[18:19]
	s_and_b64 vcc, exec, s[38:39]
	v_pk_mul_f32 v[12:13], v[12:13], v[16:17]
	s_cbranch_vccnz .LBB0_256
	s_waitcnt vmcnt(15)
	v_lshlrev_b32_e32 v18, 16, v120
	v_and_b32_e32 v19, 0xffff0000, v120
	v_lshlrev_b32_e32 v16, 16, v121
	v_and_b32_e32 v17, 0xffff0000, v121
	v_pk_add_f32 v[14:15], v[14:15], v[16:17]
	v_pk_add_f32 v[12:13], v[12:13], v[18:19]
.LBB0_256:
	s_nop 0
	s_nop 1
	v_cvt_pk_bf16_f32 v12, v12, v13
	s_nop 1
	v_cvt_pk_bf16_f32 v13, v14, v15
	global_store_dwordx2 v[136:137], v[12:13], off
	v_lshlrev_b32_e32 v12, 16, v146
	v_and_b32_e32 v13, 0xffff0000, v146
	v_lshlrev_b32_e32 v14, 16, v148
	v_and_b32_e32 v15, 0xffff0000, v148
	v_pk_mul_f32 v[10:11], v[10:11], v[14:15]
	s_and_b64 vcc, exec, s[38:39]
	v_pk_mul_f32 v[8:9], v[8:9], v[12:13]
	s_cbranch_vccnz .LBB0_258
	s_waitcnt vmcnt(15)
	v_lshlrev_b32_e32 v14, 16, v122
	v_and_b32_e32 v15, 0xffff0000, v122
	v_lshlrev_b32_e32 v12, 16, v123
	v_and_b32_e32 v13, 0xffff0000, v123
	v_pk_add_f32 v[10:11], v[10:11], v[12:13]
	v_pk_add_f32 v[8:9], v[8:9], v[14:15]
.LBB0_258:
	s_nop 0
	s_nop 1
	v_cvt_pk_bf16_f32 v8, v8, v9
	s_nop 1
	v_cvt_pk_bf16_f32 v9, v10, v11
	global_store_dwordx2 v[136:137], v[8:9], off offset:32
	v_lshlrev_b32_e32 v8, 16, v147
	v_and_b32_e32 v9, 0xffff0000, v147
	v_lshlrev_b32_e32 v10, 16, v145
	v_and_b32_e32 v11, 0xffff0000, v145
	v_pk_mul_f32 v[6:7], v[6:7], v[10:11]
	s_and_b64 vcc, exec, s[38:39]
	v_pk_mul_f32 v[4:5], v[4:5], v[8:9]
	s_cbranch_vccnz .LBB0_260
	s_waitcnt vmcnt(15)
	v_lshlrev_b32_e32 v10, 16, v124
	v_and_b32_e32 v11, 0xffff0000, v124
	v_lshlrev_b32_e32 v8, 16, v125
	v_and_b32_e32 v9, 0xffff0000, v125
	v_pk_add_f32 v[6:7], v[6:7], v[8:9]
	v_pk_add_f32 v[4:5], v[4:5], v[10:11]
.LBB0_260:
	s_nop 0
	s_nop 1
	v_cvt_pk_bf16_f32 v4, v4, v5
	s_nop 1
	v_cvt_pk_bf16_f32 v5, v6, v7
	global_store_dwordx2 v[136:137], v[4:5], off offset:64
	v_lshlrev_b32_e32 v4, 16, v144
	v_and_b32_e32 v5, 0xffff0000, v144
	v_lshlrev_b32_e32 v6, 16, v143
	v_and_b32_e32 v7, 0xffff0000, v143
	v_pk_mul_f32 v[2:3], v[2:3], v[6:7]
	s_and_b64 vcc, exec, s[38:39]
	v_pk_mul_f32 v[0:1], v[0:1], v[4:5]
	s_cbranch_vccnz .LBB0_220
	s_waitcnt vmcnt(15)
	v_lshlrev_b32_e32 v6, 16, v126
	v_and_b32_e32 v7, 0xffff0000, v126
	v_lshlrev_b32_e32 v4, 16, v127
	v_and_b32_e32 v5, 0xffff0000, v127
	v_pk_add_f32 v[2:3], v[2:3], v[4:5]
	v_pk_add_f32 v[0:1], v[0:1], v[6:7]
	s_branch .LBB0_220

.LBB0_294:
	v_ashrrev_i32_e32 v5, 31, v4
	s_waitcnt vmcnt(4)
	v_lshlrev_b64 v[16:17], 10, v[4:5]
	v_lshl_add_u64 v[16:17], v[6:7], 0, v[16:17]
	global_load_dwordx4 v[16:19], v[16:17], off
	s_mov_b32 s6, s62
	s_waitcnt vmcnt(0)
	v_pk_mul_f32 v[22:23], v[16:17], v[16:17]
	v_pk_mul_f32 v[20:21], v[18:19], v[18:19]
	v_add_f32_e32 v22, v22, v23
	v_add_f32_e32 v20, v20, v22
	v_add_f32_e32 v20, v21, v20
	s_nop 1
	v_add_f32_dpp v20, v20, v20 quad_perm:[1,0,3,2] row_mask:0xf bank_mask:0xf
	s_nop 1
	v_add_f32_dpp v20, v20, v20 quad_perm:[2,3,0,1] row_mask:0xf bank_mask:0xf
	s_nop 1
	v_add_f32_dpp v20, v20, v20 row_half_mirror row_mask:0xf bank_mask:0xf
	s_nop 1
	v_add_f32_dpp v20, v20, v20 row_mirror row_mask:0xf bank_mask:0xf
	s_nop 1
	v_add_f32_dpp v20, v20, v20 row_bcast:15 row_mask:0xa bank_mask:0xf
	s_nop 1
	v_add_f32_dpp v20, v20, v20 row_bcast:31 row_mask:0xc bank_mask:0xf
	s_nop 0
	v_readlane_b32 s100, v20, 63
	s_nop 1
	v_mov_b32_e32 v20, s100
	v_fmamk_f32 v20, v20, 0x3b800000, v196
	v_cmp_gt_f32_e32 vcc, s7, v20
	v_mul_f32_e32 v21, 0x4b800000, v20
	s_nop 0
	v_cndmask_b32_e32 v20, v20, v21, vcc
	v_rsq_f32_e32 v20, v20
	s_nop 0
	v_mul_f32_e32 v21, 0x45800000, v20
	v_cndmask_b32_e32 v20, v20, v21, vcc
	v_mul_f32_e32 v16, v16, v20
	v_mul_f32_e32 v17, v17, v20
	v_mul_f32_e32 v16, v0, v16
	v_mul_f32_e32 v17, v1, v17
	s_nop 1
	v_cvt_pk_bf16_f32 v16, v16, v17
	v_mul_f32_e32 v17, v18, v20
	v_mul_f32_e32 v18, v19, v20
	v_mul_f32_e32 v17, v2, v17
	v_mul_f32_e32 v18, v3, v18
	s_nop 1
	v_cvt_pk_bf16_f32 v17, v17, v18
	v_lshlrev_b64 v[18:19], 9, v[4:5]
	v_lshl_add_u64 v[18:19], v[8:9], 0, v[18:19]
	global_store_dwordx2 v[18:19], v[16:17], off
	s_nop 0
	v_lshl_add_u32 v4, s6, 2, v4
	v_cmp_lt_i32_e32 vcc, s8, v4
	s_or_b64 s[4:5], vcc, s[4:5]
	s_andn2_b64 exec, exec, s[4:5]
	s_cbranch_execnz .LBB0_294

.LBB0_1465:
	s_or_b64 exec, exec, s[0:1]
	global_load_dwordx2 v[34:35], v[34:35], off
	v_lshlrev_b64 v[32:33], 12, v[32:33]
	v_cmp_lt_i32_e32 vcc, v202, v201
	s_mov_b32 s0, 0x800000
	s_waitcnt vmcnt(0)
	v_lshl_add_u64 v[32:33], v[34:35], 0, v[32:33]
	v_lshl_add_u64 v[44:45], v[32:33], 0, v[176:177]
	global_load_dwordx4 v[40:43], v[44:45], off
	global_load_dwordx4 v[36:39], v[44:45], off offset:1024
	global_load_dwordx4 v[32:35], v[44:45], off offset:2048
	s_nop 0
	global_load_dwordx4 v[44:47], v[44:45], off offset:3072
	v_cndmask_b32_e32 v54, v199, v202, vcc
	v_lshlrev_b32_e32 v55, 2, v54
	v_cmp_lt_i32_e32 vcc, v203, v201
	s_waitcnt vmcnt(3)
	v_add_f32_e32 v49, 0, v40
	v_add_f32_e32 v49, v41, v49
	v_add_f32_e32 v49, v42, v49
	v_add_f32_e32 v49, v43, v49
	s_waitcnt vmcnt(2)
	v_add_f32_e32 v49, v36, v49
	v_add_f32_e32 v49, v37, v49
	v_add_f32_e32 v49, v38, v49
	v_add_f32_e32 v49, v39, v49
	s_waitcnt vmcnt(1)
	v_add_f32_e32 v49, v32, v49
	v_add_f32_e32 v49, v33, v49
	v_add_f32_e32 v49, v34, v49
	v_add_f32_e32 v49, v35, v49
	s_waitcnt vmcnt(0)
	v_add_f32_e32 v49, v44, v49
	v_add_f32_e32 v49, v45, v49
	v_add_f32_e32 v49, v46, v49
	v_add_f32_e32 v49, v47, v49
	s_nop 1
	v_add_f32_dpp v49, v49, v49 quad_perm:[1,0,3,2] row_mask:0xf bank_mask:0xf
	v_cndmask_b32_e32 v54, v199, v203, vcc
	v_lshlrev_b32_e32 v56, 2, v54
	v_cmp_lt_i32_e32 vcc, v204, v201
	s_nop 1
	v_add_f32_dpp v49, v49, v49 quad_perm:[2,3,0,1] row_mask:0xf bank_mask:0xf
	v_cndmask_b32_e32 v54, v199, v204, vcc
	v_lshlrev_b32_e32 v57, 2, v54
	v_cmp_lt_i32_e32 vcc, v205, v201
	s_nop 1
	v_add_f32_dpp v49, v49, v49 row_half_mirror row_mask:0xf bank_mask:0xf
	v_cndmask_b32_e32 v54, v199, v205, vcc
	v_lshlrev_b32_e32 v58, 2, v54
	v_cmp_lt_i32_e32 vcc, v206, v201
	s_nop 1
	v_add_f32_dpp v49, v49, v49 row_mirror row_mask:0xf bank_mask:0xf
	v_cndmask_b32_e32 v54, v199, v206, vcc
	v_lshlrev_b32_e32 v59, 2, v54
	v_cmp_lt_i32_e32 vcc, v207, v201
	s_nop 1
	v_add_f32_dpp v49, v49, v49 row_bcast:15 row_mask:0xa bank_mask:0xf
	v_cndmask_b32_e32 v54, v199, v207, vcc
	v_lshlrev_b32_e32 v60, 2, v54
	s_nop 1
	v_add_f32_dpp v49, v49, v49 row_bcast:31 row_mask:0xc bank_mask:0xf
	s_nop 0
	v_readlane_b32 s100, v49, 63
	s_nop 1
	v_mov_b32_e32 v49, s100
	v_fmamk_f32 v62, v49, 0xba800000, v41
	v_fmamk_f32 v61, v49, 0xba800000, v40
	v_mul_f32_e32 v40, v62, v62
	v_fmac_f32_e32 v40, v61, v61
	v_fmamk_f32 v42, v49, 0xba800000, v42
	v_fmac_f32_e32 v40, v42, v42
	v_fmac_f32_e32 v43, 0xba800000, v49
	v_fmac_f32_e32 v40, v43, v43
	v_fmamk_f32 v63, v49, 0xba800000, v36
	v_fmac_f32_e32 v40, v63, v63
	v_fmamk_f32 v64, v49, 0xba800000, v37
	v_fmac_f32_e32 v40, v64, v64
	v_fmamk_f32 v38, v49, 0xba800000, v38
	v_fmac_f32_e32 v40, v38, v38
	v_fmac_f32_e32 v39, 0xba800000, v49
	v_fmac_f32_e32 v40, v39, v39
	v_fmamk_f32 v65, v49, 0xba800000, v32
	v_fmac_f32_e32 v40, v65, v65
	v_fmamk_f32 v66, v49, 0xba800000, v33
	v_mul_f32_e32 v54, 0x3a800000, v49
	v_fmac_f32_e32 v40, v66, v66
	v_fmamk_f32 v34, v49, 0xba800000, v34
	v_fmac_f32_e32 v40, v34, v34
	v_fmac_f32_e32 v35, 0xba800000, v49
	v_pk_add_f32 v[32:33], v[44:45], v[54:55] op_sel_hi:[1,0] neg_lo:[0,1] neg_hi:[0,1]
	v_fmac_f32_e32 v40, v35, v35
	v_pk_mul_f32 v[36:37], v[32:33], v[32:33]
	s_nop 0
	v_add_f32_e32 v36, v36, v40
	v_add_f32_e32 v44, v37, v36
	v_pk_add_f32 v[36:37], v[46:47], v[54:55] op_sel_hi:[1,0] neg_lo:[0,1] neg_hi:[0,1]
	s_nop 0
	v_pk_mul_f32 v[40:41], v[36:37], v[36:37]
	s_nop 0
	v_add_f32_e32 v40, v40, v44
	v_add_f32_e32 v40, v41, v40
	s_nop 1
	v_add_f32_dpp v40, v40, v40 quad_perm:[1,0,3,2] row_mask:0xf bank_mask:0xf
	s_nop 1
	v_add_f32_dpp v40, v40, v40 quad_perm:[2,3,0,1] row_mask:0xf bank_mask:0xf
	s_nop 1
	v_add_f32_dpp v40, v40, v40 row_half_mirror row_mask:0xf bank_mask:0xf
	s_nop 1
	v_add_f32_dpp v40, v40, v40 row_mirror row_mask:0xf bank_mask:0xf
	s_nop 1
	v_add_f32_dpp v40, v40, v40 row_bcast:15 row_mask:0xa bank_mask:0xf
	s_nop 1
	v_add_f32_dpp v40, v40, v40 row_bcast:31 row_mask:0xc bank_mask:0xf
	s_nop 0
	v_readlane_b32 s100, v40, 63
	s_nop 1
	v_mov_b32_e32 v40, s100
	v_fmamk_f32 v40, v40, 0x3a800000, v196
	v_cmp_gt_f32_e32 vcc, s0, v40
	v_mul_f32_e32 v41, 0x4b800000, v40
	s_nop 0
	v_cndmask_b32_e32 v40, v40, v41, vcc
	v_rsq_f32_e32 v40, v40
	s_nop 0
	v_mul_f32_e32 v41, 0x45800000, v40
	v_cndmask_b32_e32 v44, v40, v41, vcc
	v_mul_f32_e32 v40, v61, v44
	v_fma_f32 v40, v0, v40, v4
	v_mul_f32_e32 v41, v62, v44
	v_mul_f32_e32 v42, v42, v44
	v_fma_f32 v41, v1, v41, v5
	v_fma_f32 v42, v2, v42, v6
	v_mul_f32_e32 v43, v43, v44
	s_nop 1
	v_cvt_pk_bf16_f32 v40, v40, v41
	v_mul_f32_e32 v38, v38, v44
	v_fma_f32 v43, v3, v43, v7
	s_nop 1
	v_cvt_pk_bf16_f32 v41, v42, v43
	global_store_dwordx2 v[52:53], v[40:41], off
	v_mul_f32_e32 v40, v63, v44
	v_fma_f32 v42, v10, v38, v14
	v_mul_f32_e32 v38, v39, v44
	v_fma_f32 v40, v8, v40, v12
	v_mul_f32_e32 v41, v64, v44
	v_fma_f32 v39, v11, v38, v15
	v_mul_f32_e32 v34, v34, v44
	v_fma_f32 v41, v9, v41, v13
	s_nop 1
	v_cvt_pk_bf16_f32 v38, v40, v41
	s_nop 1
	v_cvt_pk_bf16_f32 v39, v42, v39
	v_fma_f32 v40, v18, v34, v22
	v_mul_f32_e32 v34, v35, v44
	global_store_dwordx2 v[52:53], v[38:39], off offset:512
	v_mul_f32_e32 v38, v65, v44
	v_mul_f32_e32 v39, v66, v44
	v_fma_f32 v35, v19, v34, v23
	v_fma_f32 v38, v16, v38, v20
	v_fma_f32 v39, v17, v39, v21
	s_nop 1
	v_cvt_pk_bf16_f32 v34, v38, v39
	s_nop 1
	v_cvt_pk_bf16_f32 v35, v40, v35
	v_mul_f32_e32 v32, v32, v44
	v_mul_f32_e32 v33, v33, v44
	global_store_dwordx2 v[52:53], v[34:35], off offset:1024
	v_fma_f32 v32, v24, v32, v28
	v_fma_f32 v33, v25, v33, v29
	v_mul_f32_e32 v34, v36, v44
	v_mul_f32_e32 v35, v37, v44
	v_fma_f32 v34, v26, v34, v30
	v_fma_f32 v35, v27, v35, v31
	s_nop 1
	v_cvt_pk_bf16_f32 v32, v32, v33
	s_nop 1
	v_cvt_pk_bf16_f32 v33, v34, v35

	.amdhsa_kernel _Z8mega_fwd6Paramsii
		.amdhsa_group_segment_fixed_size 69648
		.amdhsa_private_segment_fixed_size 0
		.amdhsa_kernarg_size 488
		.amdhsa_user_sgpr_count 2
		.amdhsa_user_sgpr_dispatch_ptr 0
		.amdhsa_user_sgpr_queue_ptr 0
		.amdhsa_user_sgpr_kernarg_segment_ptr 1
		.amdhsa_user_sgpr_dispatch_id 0
		.amdhsa_user_sgpr_kernarg_preload_length 0
		.amdhsa_user_sgpr_kernarg_preload_offset 0
		.amdhsa_user_sgpr_private_segment_size 0
		.amdhsa_uses_dynamic_stack 0
		.amdhsa_enable_private_segment 0
		.amdhsa_system_sgpr_workgroup_id_x 1
		.amdhsa_system_sgpr_workgroup_id_y 0
		.amdhsa_system_sgpr_workgroup_id_z 0
		.amdhsa_system_sgpr_workgroup_info 0
		.amdhsa_system_vgpr_workitem_id 2
		.amdhsa_next_free_vgpr 254
		.amdhsa_next_free_sgpr 102
		.amdhsa_accum_offset 256
		.amdhsa_reserve_vcc 1
		.amdhsa_float_round_mode_32 0
		.amdhsa_float_round_mode_16_64 0
		.amdhsa_float_denorm_mode_32 3
		.amdhsa_float_denorm_mode_16_64 3
		.amdhsa_dx10_clamp 1
		.amdhsa_ieee_mode 1
		.amdhsa_fp16_overflow 0
		.amdhsa_tg_split 0
		.amdhsa_exception_fp_ieee_invalid_op 0
		.amdhsa_exception_fp_denorm_src 0
		.amdhsa_exception_fp_ieee_div_zero 0
		.amdhsa_exception_fp_ieee_overflow 0
		.amdhsa_exception_fp_ieee_underflow 0
		.amdhsa_exception_fp_ieee_inexact 0
		.amdhsa_exception_int_div_zero 0
	.end_amdhsa_kernel

amdhsa.kernels:
  - .agpr_count:     0
    .args:
      - .offset:         0
        .size:           224
        .value_kind:     by_value
      - .offset:         224
        .size:           4
        .value_kind:     by_value
      - .offset:         228
        .size:           4
        .value_kind:     by_value
      - .offset:         232
        .size:           4
        .value_kind:     hidden_block_count_x
      - .offset:         236
        .size:           4
        .value_kind:     hidden_block_count_y
      - .offset:         240
        .size:           4
        .value_kind:     hidden_block_count_z
      - .offset:         244
        .size:           2
        .value_kind:     hidden_group_size_x
      - .offset:         246
        .size:           2
        .value_kind:     hidden_group_size_y
      - .offset:         248
        .size:           2
        .value_kind:     hidden_group_size_z
      - .offset:         250
        .size:           2
        .value_kind:     hidden_remainder_x
      - .offset:         252
        .size:           2
        .value_kind:     hidden_remainder_y
      - .offset:         254
        .size:           2
        .value_kind:     hidden_remainder_z
      - .offset:         272
        .size:           8
        .value_kind:     hidden_global_offset_x
      - .offset:         280
        .size:           8
        .value_kind:     hidden_global_offset_y
      - .offset:         288
        .size:           8
        .value_kind:     hidden_global_offset_z
      - .offset:         296
        .size:           2
        .value_kind:     hidden_grid_dims
      - .offset:         320
        .size:           8
        .value_kind:     hidden_multigrid_sync_arg
    .group_segment_fixed_size: 69648
    .kernarg_segment_align: 8
    .kernarg_segment_size: 488
    .language:       OpenCL C
    .language_version:
      - 2
      - 0
    .max_flat_workgroup_size: 256
    .name:           _Z8mega_fwd6Paramsii
    .private_segment_fixed_size: 0
    .sgpr_count:     108
    .sgpr_spill_count: 136
    .symbol:         _Z8mega_fwd6Paramsii.kd
    .uniform_work_group_size: 1
    .uses_dynamic_stack: false
    .vgpr_count:     254
    .vgpr_spill_count: 0
    .wavefront_size: 64
